# xtop: grid barrier top level without returning atomic / generation word (leaders add to one counter, all poll it >= nx*(gen+1)); entry shift 9 dwords for layout
# baseline (speedup 1.0000x reference)
; #define LAS __attribute__((address_space(3)))
; __device__ __forceinline__ unsigned xb_add(unsigned* p, unsigned v) { return __hip_atomic_fetch_add(p, v, __ATOMIC_RELAXED, __HIP_MEMORY_SCOPE_AGENT); }
; __device__ __forceinline__ unsigned xb_xcc_id() { return (unsigned)__builtin_amdgcn_s_getreg((3 << 11) | 20) & 0xFu; }
; __device__ __forceinline__ XcdBarrier xcd_barrier_post(unsigned* bar, volatile LAS unsigned* st) {
;     XcdBarrier b; b.bar = bar; b.x = xb_xcc_id(); b.st = st;
;     if (threadIdx.x == 0) (void)xb_add(&bar[XB_XCNT(b.x)], 1u);
;     return b;
; }
; __global__ void __launch_bounds__(512, 2) mega(Params P, int ph0, int ph1) {
;     extern __shared__ __attribute__((aligned(16))) unsigned char shm[];
;     __shared__ uint4 xb_words;
;     if (threadIdx.x == 0) xb_words = make_uint4(0u, 0u, 0u, 0u);
;     __syncthreads();
;     const XcdBarrier xb = xcd_barrier_post((unsigned*)(P.ws + O_BAR), (volatile LAS unsigned*)&xb_words);
_Z4mega6Paramsii:
	s_nop 0
	s_nop 0
	s_nop 0
	s_nop 0
	s_nop 0
	s_nop 0
	s_nop 0
	s_nop 0
	s_nop 0
	s_load_dwordx2 s[88:89], s[0:1], 0xd0
	s_mov_b32 s84, s2
	s_mov_b64 s[86:87], s[0:1]
	v_cmp_eq_u32_e64 s[92:93], 0, v0
	s_and_saveexec_b64 s[4:5], s[92:93]
	v_mov_b32_e32 v2, 0
	v_mov_b32_e32 v3, v2
	v_mov_b32_e32 v4, v2
	v_mov_b32_e32 v5, v2
	ds_write_b128 v2, v[2:5]
	s_or_b64 exec, exec, s[4:5]
	s_waitcnt lgkmcnt(0)
	s_barrier
	s_add_u32 s90, s88, 0x2e9d8000
	s_getreg_b32 s0, hwreg(HW_REG_XCC_ID, 0, 4)
	s_addc_u32 s91, s89, 0
	s_and_b32 s85, s0, 15
	s_and_saveexec_b64 s[4:5], s[92:93]
	s_cbranch_execz .LBB0_5
	s_mov_b64 s[6:7], exec
	v_mbcnt_lo_u32_b32 v1, s6, 0
	v_mbcnt_hi_u32_b32 v1, s7, v1
	v_cmp_eq_u32_e32 vcc, 0, v1
	s_and_b64 s[0:1], exec, vcc
	s_mov_b64 exec, s[0:1]
	s_cbranch_execz .LBB0_5
	s_lshl_b32 s0, s85, 8
	s_bcnt1_i32_b64 s1, s[6:7]
	v_mov_b32_e32 v1, s0
	v_mov_b32_e32 v2, s1
	global_atomic_add v1, v2, s[90:91] offset:1024

; __device__ __forceinline__ unsigned xb_ld(unsigned* p)              { return __hip_atomic_load(p, __ATOMIC_RELAXED, __HIP_MEMORY_SCOPE_AGENT); }
; __device__ __forceinline__ unsigned xb_add(unsigned* p, unsigned v) { return __hip_atomic_fetch_add(p, v, __ATOMIC_RELAXED, __HIP_MEMORY_SCOPE_AGENT); }
; #define XB_SPIN(cond, bar) do { unsigned _sp = 0; while (cond) {   \
;     if ((++_sp & 255u) == 0u) { if (xb_ld(&(bar)[XB_TMO])) break; if (_sp > XB_SPIN_CAP) { atomicAdd(&(bar)[XB_TMO], 1u); break; } } } } while (0)
; __device__ __forceinline__ void xcd_barrier(const XcdBarrier& b) {
;     ...
;         const unsigned old = xb_add(&bar[XB_XSUB(b.x)], 1u);
;         const unsigned gen = old / nloc;
;         if (old + 1u == (gen + 1u) * nloc) {
;             __builtin_amdgcn_fence(__ATOMIC_RELEASE, "agent");
;             asm volatile("s_waitcnt vmcnt(0)" ::: "memory");
;             const unsigned og = xb_add(&bar[XB_TOP], 1u);
;             const unsigned tg = og / nx;
;             if (og + 1u == (tg + 1u) * nx) xb_add(&bar[XB_TOPGEN], 1u);
;             else XB_SPIN(xb_ld(&bar[XB_TOPGEN]) == tg, bar);
;             __builtin_amdgcn_fence(__ATOMIC_ACQUIRE, "agent");
;             xb_add(&bar[XB_XGEN(b.x)], 1u);
;             asm volatile("s_waitcnt vmcnt(0)" ::: "memory");
;         } else {
;             XB_SPIN(xb_ld(&bar[XB_XGEN(b.x)]) == gen, bar);
.LBB0_25:
	s_or_b64 exec, exec, s[12:13]
	v_cvt_f32_u32_e32 v5, v3
	s_waitcnt vmcnt(0)
	v_readfirstlane_b32 s0, v4
	v_sub_u32_e32 v4, 0, v3
	v_rcp_iflag_f32_e32 v5, v5
	v_add_u32_e32 v6, s0, v1
	v_mul_f32_e32 v5, 0x4f7ffffe, v5
	v_cvt_u32_f32_e32 v5, v5
	v_mul_lo_u32 v1, v4, v5
	v_mul_hi_u32 v1, v5, v1
	v_add_u32_e32 v1, v5, v1
	v_mul_hi_u32 v1, v6, v1
	v_mul_lo_u32 v4, v1, v3
	v_sub_u32_e32 v4, v6, v4
	v_add_u32_e32 v5, 1, v1
	v_cmp_ge_u32_e32 vcc, v4, v3
	s_nop 1
	v_cndmask_b32_e32 v1, v1, v5, vcc
	v_sub_u32_e32 v5, v4, v3
	v_cndmask_b32_e32 v4, v4, v5, vcc
	v_add_u32_e32 v5, 1, v1
	v_cmp_ge_u32_e32 vcc, v4, v3
	v_add_u32_e32 v4, 1, v6
	s_nop 0
	v_cndmask_b32_e32 v1, v1, v5, vcc
	v_mul_lo_u32 v5, v3, v1
	v_add_u32_e32 v3, v5, v3
	v_cmp_ne_u32_e32 vcc, v4, v3
	s_and_saveexec_b64 s[0:1], vcc
	s_xor_b64 s[8:9], exec, s[0:1]
	s_cbranch_execz .LBB0_39
	s_waitcnt lgkmcnt(0)
	v_mad_u32_u24 v5, v2, v1, v2
	v_mov_b32_e32 v2, 0x3000
	global_load_dword v2, v2, s[90:91] offset:1024 sc1
	s_add_u32 s16, s90, 0x3400
	s_addc_u32 s17, s91, 0
	s_waitcnt vmcnt(0)
	v_cmp_gt_u32_e32 vcc, v5, v2
	s_and_saveexec_b64 s[12:13], vcc
	s_cbranch_execz .LBB0_38
	s_add_u32 s14, s88, 0x2e9d8200
	s_addc_u32 s15, s89, 0
	s_mov_b32 s0, 1
	s_mov_b64 s[18:19], 0
	v_mov_b32_e32 v2, 0
	s_branch .LBB0_29

; __device__ __forceinline__ unsigned xb_ld(unsigned* p)              { return __hip_atomic_load(p, __ATOMIC_RELAXED, __HIP_MEMORY_SCOPE_AGENT); }
; __device__ __forceinline__ unsigned xb_add(unsigned* p, unsigned v) { return __hip_atomic_fetch_add(p, v, __ATOMIC_RELAXED, __HIP_MEMORY_SCOPE_AGENT); }
; #define XB_SPIN(cond, bar) do { unsigned _sp = 0; while (cond) {   \
;     if ((++_sp & 255u) == 0u) { if (xb_ld(&(bar)[XB_TMO])) break; if (_sp > XB_SPIN_CAP) { atomicAdd(&(bar)[XB_TMO], 1u); break; } } } } while (0)
; __device__ __forceinline__ void xcd_barrier(const XcdBarrier& b) {
;     ...
;             else XB_SPIN(xb_ld(&bar[XB_TOPGEN]) == tg, bar);
;             __builtin_amdgcn_fence(__ATOMIC_ACQUIRE, "agent");
;             xb_add(&bar[XB_XGEN(b.x)], 1u);
;             asm volatile("s_waitcnt vmcnt(0)" ::: "memory");
;         } else {
;             XB_SPIN(xb_ld(&bar[XB_XGEN(b.x)]) == gen, bar);
.LBB0_31:
	global_load_dword v3, v2, s[16:17] sc1
	s_add_i32 s0, s0, 1
	s_mov_b64 s[24:25], -1
	s_waitcnt vmcnt(0)
	v_cmp_le_u32_e32 vcc, v5, v3
	s_orn2_b64 s[22:23], vcc, exec
	s_branch .LBB0_28

; __device__ __forceinline__ unsigned xb_ld(unsigned* p)              { return __hip_atomic_load(p, __ATOMIC_RELAXED, __HIP_MEMORY_SCOPE_AGENT); }
; __device__ __forceinline__ unsigned xb_add(unsigned* p, unsigned v) { return __hip_atomic_fetch_add(p, v, __ATOMIC_RELAXED, __HIP_MEMORY_SCOPE_AGENT); }
; #define XB_SPIN(cond, bar) do { unsigned _sp = 0; while (cond) {   \
;     if ((++_sp & 255u) == 0u) { if (xb_ld(&(bar)[XB_TMO])) break; if (_sp > XB_SPIN_CAP) { atomicAdd(&(bar)[XB_TMO], 1u); break; } } } } while (0)
; __device__ __forceinline__ void xcd_barrier(const XcdBarrier& b) {
;     ...
;             __builtin_amdgcn_fence(__ATOMIC_RELEASE, "agent");
;             asm volatile("s_waitcnt vmcnt(0)" ::: "memory");
;             const unsigned og = xb_add(&bar[XB_TOP], 1u);
;             const unsigned tg = og / nx;
;             if (og + 1u == (tg + 1u) * nx) xb_add(&bar[XB_TOPGEN], 1u);
;             else XB_SPIN(xb_ld(&bar[XB_TOPGEN]) == tg, bar);
;             __builtin_amdgcn_fence(__ATOMIC_ACQUIRE, "agent");
;             xb_add(&bar[XB_XGEN(b.x)], 1u);
;             asm volatile("s_waitcnt vmcnt(0)" ::: "memory");
;         } else {
;             XB_SPIN(xb_ld(&bar[XB_XGEN(b.x)]) == gen, bar);
;             __builtin_amdgcn_fence(__ATOMIC_ACQUIRE, "agent");
;             asm volatile("s_waitcnt vmcnt(0)" ::: "memory");
.LBB0_39:
	s_andn2_saveexec_b64 s[0:1], s[8:9]
	s_cbranch_execz .LBB0_59
	buffer_wbl2 sc1
	s_waitcnt vmcnt(0) lgkmcnt(0)
	v_mad_u32_u24 v5, v2, v1, v2
	v_mov_b32_e32 v3, 0x2e9db000
	v_mov_b32_e32 v4, 1
	global_atomic_add v3, v4, s[88:89] offset:1024
	s_add_u32 s12, s88, 0x2e9db400
	s_addc_u32 s13, s89, 0
	v_mov_b32_e32 v2, 0
	s_mov_b32 s0, 0
.Lxt_spin_0:
	global_load_dword v3, v2, s[12:13] sc1
	s_add_u32 s0, s0, 1
	s_waitcnt vmcnt(0)
	v_cmp_le_u32_e32 vcc, v5, v3
	s_cbranch_vccnz .Lxt_done_0
	s_cmp_lt_u32 s0, 0x400000
	s_cbranch_scc1 .Lxt_spin_0
.Lxt_done_0:
	buffer_inv sc1
	s_waitcnt vmcnt(0)
